# static K-loop priority raise for the workgroup with id bit 8 clear (reverse polarity)
# baseline (speedup 1.0000x reference)
; template <class Epi>
; __device__ __forceinline__ void gemm_tile(const bf16_t* __restrict__ A, const bf16_t* __restrict__ Bt, int K, int row0, int col0, const Epi& epi, char* smem,
;                                           bool prefetched, bool nvalid, int nrow0, int ncol0) {
;     ...
;     int offA[4][2], offB[4][2];
; #pragma unroll
;     for (int m = 0; m < 4; ++m)
; #pragma unroll
;         for (int ks = 0; ks < 2; ++ks) { const int cx = ((ks * 4 + fq) ^ ((fr >> 1) & 7)) * 16;
;             offA[m][ks] = (wr * 64 + m * 16 + fr) * 128 + cx;
;             offB[m][ks] = TILE_B + (wc * 64 + (m >> 1) * 32 + 8 * (fr >> 2) + 4 * (m & 1) + (fr & 3)) * 128 + cx; }
;     if (prefetched) {
;         if (Epi::STAGED) asm volatile("s_waitcnt vmcnt(8)" ::: "memory");
;         else asm volatile("s_waitcnt vmcnt(0)" ::: "memory");
;     } else {
;         GLDS_STAGE(0, pA, pB, 0);
;         asm volatile("s_waitcnt vmcnt(0)" ::: "memory");
;     }
;     __syncthreads();
;     const int nk = K >> 6;
;     for (int kt = 0; kt < nk; ++kt) {
;         const int cur = kt & 1;
;         if (kt + 1 < nk) GLDS_STAGE(cur ^ 1, pA, pB, kt + 1);
;         const char* cb = smem + cur * 2 * TILE_B;
; #pragma unroll
;         for (int ks = 0; ks < 2; ++ks) {
;             bf16x8 a[4], b[4];
; #pragma unroll
;             for (int m = 0; m < 4; ++m) a[m] = *(const bf16x8*)(cb + offA[m][ks]);
; #pragma unroll
;             for (int n = 0; n < 4; ++n) b[n] = *(const bf16x8*)(cb + offB[n][ks]);
.LBB0_154:
	v_readfirstlane_b32 s98, v64
	v_readfirstlane_b32 s99, v65
	v_readfirstlane_b32 s10, v66
	v_readfirstlane_b32 s100, v72
	v_readfirstlane_b32 s101, v73
	v_readfirstlane_b32 s13, v149
	s_nop 3
	s_sub_u32 s14, s10, s98
	s_and_b32 s98, s98, 0xffffff80
	s_and_b32 s100, s100, 0xffffff80
	s_nop 1
	v_subrev_u32_e32 v254, s98, v64
	v_subrev_u32_e32 v255, s100, v72
	s_add_i32 s12, s13, 0x8000
	s_mov_b32 m0, s12
	s_nop 0
	global_load_lds_dwordx4 v254, s[98:99]
	s_add_i32 m0, s12, 0x1000
	s_add_u32 s10, s98, s14
	s_addc_u32 s11, s99, 0
	global_load_lds_dwordx4 v254, s[10:11]
	s_add_i32 m0, s12, 0x2000
	s_add_u32 s10, s10, s14
	s_addc_u32 s11, s11, 0
	global_load_lds_dwordx4 v254, s[10:11]
	s_add_i32 m0, s12, 0x3000
	s_add_u32 s10, s10, s14
	s_addc_u32 s11, s11, 0
	global_load_lds_dwordx4 v254, s[10:11]
	s_add_u32 s98, s98, 0x80
	s_addc_u32 s99, s99, 0
	ds_read_b128 v[182:185], v139
	ds_read_b128 v[64:67], v142 offset:16384
	ds_read_b128 v[68:71], v142 offset:16896
	ds_read_b128 v[72:75], v142 offset:20480
	ds_read_b128 v[76:79], v142 offset:20992
	ds_read_b128 v[186:189], v139 offset:2048
	ds_read_b128 v[246:249], v139 offset:4096
	ds_read_b128 v[250:253], v139 offset:6144
	v_readlane_b32 s8, v245, 0
	s_nop 3
	s_bitcmp0_b32 s8, 8
	s_cbranch_scc1 .Lgk_y_154
	s_setprio 1
	s_branch .Lgk_g_154

; template <class Epi>
; __device__ __forceinline__ void gemm_tile(const bf16_t* __restrict__ A, const bf16_t* __restrict__ Bt, int K, int row0, int col0, const Epi& epi, char* smem,
;                                           bool prefetched, bool nvalid, int nrow0, int ncol0) {
;     ...
;     int offA[4][2], offB[4][2];
; #pragma unroll
;     for (int m = 0; m < 4; ++m)
; #pragma unroll
;         for (int ks = 0; ks < 2; ++ks) { const int cx = ((ks * 4 + fq) ^ ((fr >> 1) & 7)) * 16;
;             offA[m][ks] = (wr * 64 + m * 16 + fr) * 128 + cx;
;             offB[m][ks] = TILE_B + (wc * 64 + (m >> 1) * 32 + 8 * (fr >> 2) + 4 * (m & 1) + (fr & 3)) * 128 + cx; }
;     if (prefetched) {
;         if (Epi::STAGED) asm volatile("s_waitcnt vmcnt(8)" ::: "memory");
;         else asm volatile("s_waitcnt vmcnt(0)" ::: "memory");
;     } else {
;         GLDS_STAGE(0, pA, pB, 0);
;         asm volatile("s_waitcnt vmcnt(0)" ::: "memory");
;     }
;     __syncthreads();
;     const int nk = K >> 6;
;     for (int kt = 0; kt < nk; ++kt) {
;         const int cur = kt & 1;
;         if (kt + 1 < nk) GLDS_STAGE(cur ^ 1, pA, pB, kt + 1);
;         const char* cb = smem + cur * 2 * TILE_B;
; #pragma unroll
;         for (int ks = 0; ks < 2; ++ks) {
;             bf16x8 a[4], b[4];
; #pragma unroll
;             for (int m = 0; m < 4; ++m) a[m] = *(const bf16x8*)(cb + offA[m][ks]);
; #pragma unroll
;             for (int n = 0; n < 4; ++n) b[n] = *(const bf16x8*)(cb + offB[n][ks]);
.LBB0_197:
	v_readfirstlane_b32 s98, v106
	v_readfirstlane_b32 s99, v107
	v_readfirstlane_b32 s8, v108
	v_readfirstlane_b32 s100, v120
	v_readfirstlane_b32 s101, v121
	v_readfirstlane_b32 s11, v149
	s_nop 3
	s_sub_u32 s15, s8, s98
	s_and_b32 s98, s98, 0xffffff80
	s_and_b32 s100, s100, 0xffffff80
	s_nop 1
	v_subrev_u32_e32 v254, s98, v106
	v_subrev_u32_e32 v255, s100, v120
	s_add_i32 s10, s11, 0x8000
	s_mov_b32 m0, s10
	s_nop 0
	global_load_lds_dwordx4 v254, s[98:99]
	s_add_i32 m0, s10, 0x1000
	s_add_u32 s8, s98, s15
	s_addc_u32 s9, s99, 0
	global_load_lds_dwordx4 v254, s[8:9]
	s_add_i32 m0, s10, 0x2000
	s_add_u32 s8, s8, s15
	s_addc_u32 s9, s9, 0
	global_load_lds_dwordx4 v254, s[8:9]
	s_add_i32 m0, s10, 0x3000
	s_add_u32 s8, s8, s15
	s_addc_u32 s9, s9, 0
	global_load_lds_dwordx4 v254, s[8:9]
	s_add_u32 s98, s98, 0x80
	s_addc_u32 s99, s99, 0
	ds_read_b128 v[188:191], v117
	ds_read_b128 v[106:109], v130 offset:16384
	ds_read_b128 v[118:121], v130 offset:16896
	ds_read_b128 v[122:125], v130 offset:20480
	ds_read_b128 v[168:171], v130 offset:20992
	ds_read_b128 v[192:195], v117 offset:2048
	ds_read_b128 v[196:199], v117 offset:4096
	ds_read_b128 v[246:249], v117 offset:6144
	v_readlane_b32 s6, v245, 0
	s_nop 3
	s_bitcmp0_b32 s6, 8
	s_cbranch_scc1 .Lgk_y_197
	s_setprio 1
	s_branch .Lgk_g_197

; template <class Epi>
; __device__ __forceinline__ void gemm_tile(const bf16_t* __restrict__ A, const bf16_t* __restrict__ Bt, int K, int row0, int col0, const Epi& epi, char* smem,
;                                           bool prefetched, bool nvalid, int nrow0, int ncol0) {
;     ...
;     int offA[4][2], offB[4][2];
; #pragma unroll
;     for (int m = 0; m < 4; ++m)
; #pragma unroll
;         for (int ks = 0; ks < 2; ++ks) { const int cx = ((ks * 4 + fq) ^ ((fr >> 1) & 7)) * 16;
;             offA[m][ks] = (wr * 64 + m * 16 + fr) * 128 + cx;
;             offB[m][ks] = TILE_B + (wc * 64 + (m >> 1) * 32 + 8 * (fr >> 2) + 4 * (m & 1) + (fr & 3)) * 128 + cx; }
;     if (prefetched) {
;         if (Epi::STAGED) asm volatile("s_waitcnt vmcnt(8)" ::: "memory");
;         else asm volatile("s_waitcnt vmcnt(0)" ::: "memory");
;     } else {
;         GLDS_STAGE(0, pA, pB, 0);
;         asm volatile("s_waitcnt vmcnt(0)" ::: "memory");
;     }
;     __syncthreads();
;     const int nk = K >> 6;
;     for (int kt = 0; kt < nk; ++kt) {
;         const int cur = kt & 1;
;         if (kt + 1 < nk) GLDS_STAGE(cur ^ 1, pA, pB, kt + 1);
;         const char* cb = smem + cur * 2 * TILE_B;
; #pragma unroll
;         for (int ks = 0; ks < 2; ++ks) {
;             bf16x8 a[4], b[4];
; #pragma unroll
;             for (int m = 0; m < 4; ++m) a[m] = *(const bf16x8*)(cb + offA[m][ks]);
; #pragma unroll
;             for (int n = 0; n < 4; ++n) b[n] = *(const bf16x8*)(cb + offB[n][ks]);
.LBB0_460:
	v_readfirstlane_b32 s98, v94
	v_readfirstlane_b32 s99, v95
	v_readfirstlane_b32 s8, v96
	v_readfirstlane_b32 s100, v102
	v_readfirstlane_b32 s101, v103
	v_readfirstlane_b32 s12, v149
	s_nop 3
	s_sub_u32 s13, s8, s98
	s_and_b32 s98, s98, 0xffffff80
	s_and_b32 s100, s100, 0xffffff80
	s_nop 1
	v_subrev_u32_e32 v254, s98, v94
	v_subrev_u32_e32 v255, s100, v102
	s_add_i32 s11, s12, 0x8000
	s_mov_b32 m0, s11
	s_nop 0
	global_load_lds_dwordx4 v254, s[98:99]
	s_add_i32 m0, s11, 0x1000
	s_add_u32 s8, s98, s13
	s_addc_u32 s9, s99, 0
	global_load_lds_dwordx4 v254, s[8:9]
	s_add_i32 m0, s11, 0x2000
	s_add_u32 s8, s8, s13
	s_addc_u32 s9, s9, 0
	global_load_lds_dwordx4 v254, s[8:9]
	s_add_i32 m0, s11, 0x3000
	s_add_u32 s8, s8, s13
	s_addc_u32 s9, s9, 0
	global_load_lds_dwordx4 v254, s[8:9]
	s_add_u32 s98, s98, 0x80
	s_addc_u32 s99, s99, 0
	ds_read_b128 v[174:177], v110
	ds_read_b128 v[94:97], v87 offset:16384
	ds_read_b128 v[98:101], v87 offset:16896
	ds_read_b128 v[102:105], v87 offset:20480
	ds_read_b128 v[106:109], v87 offset:20992
	ds_read_b128 v[178:181], v110 offset:2048
	ds_read_b128 v[246:249], v110 offset:4096
	ds_read_b128 v[250:253], v110 offset:6144
	v_readlane_b32 s5, v245, 0
	s_nop 3
	s_bitcmp0_b32 s5, 8
	s_cbranch_scc1 .Lgk_y_460
	s_setprio 1
	s_branch .Lgk_g_460

; template <class Epi>
; __device__ __forceinline__ void gemm_tile(const bf16_t* __restrict__ A, const bf16_t* __restrict__ Bt, int K, int row0, int col0, const Epi& epi, char* smem,
;                                           bool prefetched, bool nvalid, int nrow0, int ncol0) {
;     ...
;     int offA[4][2], offB[4][2];
; #pragma unroll
;     for (int m = 0; m < 4; ++m)
; #pragma unroll
;         for (int ks = 0; ks < 2; ++ks) { const int cx = ((ks * 4 + fq) ^ ((fr >> 1) & 7)) * 16;
;             offA[m][ks] = (wr * 64 + m * 16 + fr) * 128 + cx;
;             offB[m][ks] = TILE_B + (wc * 64 + (m >> 1) * 32 + 8 * (fr >> 2) + 4 * (m & 1) + (fr & 3)) * 128 + cx; }
;     if (prefetched) {
;         if (Epi::STAGED) asm volatile("s_waitcnt vmcnt(8)" ::: "memory");
;         else asm volatile("s_waitcnt vmcnt(0)" ::: "memory");
;     } else {
;         GLDS_STAGE(0, pA, pB, 0);
;         asm volatile("s_waitcnt vmcnt(0)" ::: "memory");
;     }
;     __syncthreads();
;     const int nk = K >> 6;
;     for (int kt = 0; kt < nk; ++kt) {
;         const int cur = kt & 1;
;         if (kt + 1 < nk) GLDS_STAGE(cur ^ 1, pA, pB, kt + 1);
;         const char* cb = smem + cur * 2 * TILE_B;
; #pragma unroll
;         for (int ks = 0; ks < 2; ++ks) {
;             bf16x8 a[4], b[4];
; #pragma unroll
;             for (int m = 0; m < 4; ++m) a[m] = *(const bf16x8*)(cb + offA[m][ks]);
; #pragma unroll
;             for (int n = 0; n < 4; ++n) b[n] = *(const bf16x8*)(cb + offB[n][ks]);
.LBB0_563:
	v_readfirstlane_b32 s98, v110
	v_readfirstlane_b32 s99, v111
	v_readfirstlane_b32 s10, v118
	v_readfirstlane_b32 s100, v124
	v_readfirstlane_b32 s101, v125
	v_readfirstlane_b32 s17, v149
	s_nop 3
	s_sub_u32 s18, s10, s98
	s_and_b32 s98, s98, 0xffffff80
	s_and_b32 s100, s100, 0xffffff80
	s_nop 1
	v_subrev_u32_e32 v254, s98, v110
	v_subrev_u32_e32 v255, s100, v124
	s_add_i32 s13, s17, 0x8000
	s_mov_b32 m0, s13
	s_nop 0
	global_load_lds_dwordx4 v254, s[98:99]
	s_add_i32 m0, s13, 0x1000
	s_add_u32 s10, s98, s18
	s_addc_u32 s11, s99, 0
	global_load_lds_dwordx4 v254, s[10:11]
	s_add_i32 m0, s13, 0x2000
	s_add_u32 s10, s10, s18
	s_addc_u32 s11, s11, 0
	global_load_lds_dwordx4 v254, s[10:11]
	s_add_i32 m0, s13, 0x3000
	s_add_u32 s10, s10, s18
	s_addc_u32 s11, s11, 0
	global_load_lds_dwordx4 v254, s[10:11]
	s_add_u32 s98, s98, 0x80
	s_addc_u32 s99, s99, 0
	ds_read_b128 v[192:195], v85
	ds_read_b128 v[118:121], v142 offset:16384
	ds_read_b128 v[122:125], v142 offset:16896
	ds_read_b128 v[126:129], v142 offset:20480
	ds_read_b128 v[172:175], v142 offset:20992
	ds_read_b128 v[196:199], v85 offset:2048
	ds_read_b128 v[246:249], v85 offset:4096
	ds_read_b128 v[250:253], v85 offset:6144
	v_readlane_b32 s9, v245, 0
	s_nop 3
	s_bitcmp0_b32 s9, 8
	s_cbranch_scc1 .Lgk_y_563
	s_setprio 1
	s_branch .Lgk_g_563

; template <class Epi>
; __device__ __forceinline__ void gemm_tile(const bf16_t* __restrict__ A, const bf16_t* __restrict__ Bt, int K, int row0, int col0, const Epi& epi, char* smem,
;                                           bool prefetched, bool nvalid, int nrow0, int ncol0) {
;     ...
;     int offA[4][2], offB[4][2];
; #pragma unroll
;     for (int m = 0; m < 4; ++m)
; #pragma unroll
;         for (int ks = 0; ks < 2; ++ks) { const int cx = ((ks * 4 + fq) ^ ((fr >> 1) & 7)) * 16;
;             offA[m][ks] = (wr * 64 + m * 16 + fr) * 128 + cx;
;             offB[m][ks] = TILE_B + (wc * 64 + (m >> 1) * 32 + 8 * (fr >> 2) + 4 * (m & 1) + (fr & 3)) * 128 + cx; }
;     if (prefetched) {
;         if (Epi::STAGED) asm volatile("s_waitcnt vmcnt(8)" ::: "memory");
;         else asm volatile("s_waitcnt vmcnt(0)" ::: "memory");
;     } else {
;         GLDS_STAGE(0, pA, pB, 0);
;         asm volatile("s_waitcnt vmcnt(0)" ::: "memory");
;     }
;     __syncthreads();
;     const int nk = K >> 6;
;     for (int kt = 0; kt < nk; ++kt) {
;         const int cur = kt & 1;
;         if (kt + 1 < nk) GLDS_STAGE(cur ^ 1, pA, pB, kt + 1);
;         const char* cb = smem + cur * 2 * TILE_B;
; #pragma unroll
;         for (int ks = 0; ks < 2; ++ks) {
;             bf16x8 a[4], b[4];
; #pragma unroll
;             for (int m = 0; m < 4; ++m) a[m] = *(const bf16x8*)(cb + offA[m][ks]);
; #pragma unroll
;             for (int n = 0; n < 4; ++n) b[n] = *(const bf16x8*)(cb + offB[n][ks]);
.LBB0_619:
	v_readfirstlane_b32 s98, v92
	v_readfirstlane_b32 s99, v93
	v_readfirstlane_b32 s8, v94
	v_readfirstlane_b32 s100, v100
	v_readfirstlane_b32 s101, v101
	v_readfirstlane_b32 s12, v149
	s_nop 3
	s_sub_u32 s13, s8, s98
	s_and_b32 s98, s98, 0xffffff80
	s_and_b32 s100, s100, 0xffffff80
	s_nop 1
	v_subrev_u32_e32 v254, s98, v92
	v_subrev_u32_e32 v255, s100, v100
	s_add_i32 s11, s12, 0x8000
	s_mov_b32 m0, s11
	s_nop 0
	global_load_lds_dwordx4 v254, s[98:99]
	s_add_i32 m0, s11, 0x1000
	s_add_u32 s8, s98, s13
	s_addc_u32 s9, s99, 0
	global_load_lds_dwordx4 v254, s[8:9]
	s_add_i32 m0, s11, 0x2000
	s_add_u32 s8, s8, s13
	s_addc_u32 s9, s9, 0
	global_load_lds_dwordx4 v254, s[8:9]
	s_add_i32 m0, s11, 0x3000
	s_add_u32 s8, s8, s13
	s_addc_u32 s9, s9, 0
	global_load_lds_dwordx4 v254, s[8:9]
	s_add_u32 s98, s98, 0x80
	s_addc_u32 s99, s99, 0
	ds_read_b128 v[174:177], v108
	ds_read_b128 v[92:95], v110 offset:16384
	ds_read_b128 v[96:99], v110 offset:16896
	ds_read_b128 v[100:103], v110 offset:20480
	ds_read_b128 v[104:107], v110 offset:20992
	ds_read_b128 v[178:181], v108 offset:2048
	ds_read_b128 v[246:249], v108 offset:4096
	ds_read_b128 v[250:253], v108 offset:6144
	v_readlane_b32 s3, v245, 0
	s_nop 3
	s_bitcmp0_b32 s3, 8
	s_cbranch_scc1 .Lgk_y_619
	s_setprio 1
	s_branch .Lgk_g_619

; template <class Epi>
; __device__ __forceinline__ void gemm_tile(const bf16_t* __restrict__ A, const bf16_t* __restrict__ Bt, int K, int row0, int col0, const Epi& epi, char* smem,
;                                           bool prefetched, bool nvalid, int nrow0, int ncol0) {
;     ...
;     int offA[4][2], offB[4][2];
; #pragma unroll
;     for (int m = 0; m < 4; ++m)
; #pragma unroll
;         for (int ks = 0; ks < 2; ++ks) { const int cx = ((ks * 4 + fq) ^ ((fr >> 1) & 7)) * 16;
;             offA[m][ks] = (wr * 64 + m * 16 + fr) * 128 + cx;
;             offB[m][ks] = TILE_B + (wc * 64 + (m >> 1) * 32 + 8 * (fr >> 2) + 4 * (m & 1) + (fr & 3)) * 128 + cx; }
;     if (prefetched) {
;         if (Epi::STAGED) asm volatile("s_waitcnt vmcnt(8)" ::: "memory");
;         else asm volatile("s_waitcnt vmcnt(0)" ::: "memory");
;     } else {
;         GLDS_STAGE(0, pA, pB, 0);
;         asm volatile("s_waitcnt vmcnt(0)" ::: "memory");
;     }
;     __syncthreads();
;     const int nk = K >> 6;
;     for (int kt = 0; kt < nk; ++kt) {
;         const int cur = kt & 1;
;         if (kt + 1 < nk) GLDS_STAGE(cur ^ 1, pA, pB, kt + 1);
;         const char* cb = smem + cur * 2 * TILE_B;
; #pragma unroll
;         for (int ks = 0; ks < 2; ++ks) {
;             bf16x8 a[4], b[4];
; #pragma unroll
;             for (int m = 0; m < 4; ++m) a[m] = *(const bf16x8*)(cb + offA[m][ks]);
; #pragma unroll
;             for (int n = 0; n < 4; ++n) b[n] = *(const bf16x8*)(cb + offB[n][ks]);
.LBB0_723:
	v_readfirstlane_b32 s98, v64
	v_readfirstlane_b32 s99, v65
	v_readfirstlane_b32 s12, v66
	v_readfirstlane_b32 s100, v72
	v_readfirstlane_b32 s101, v73
	v_readfirstlane_b32 s15, v149
	s_nop 3
	s_sub_u32 s16, s12, s98
	s_and_b32 s98, s98, 0xffffff80
	s_and_b32 s100, s100, 0xffffff80
	s_nop 1
	v_subrev_u32_e32 v254, s98, v64
	v_subrev_u32_e32 v255, s100, v72
	s_add_i32 s14, s15, 0x8000
	s_mov_b32 m0, s14
	s_nop 0
	global_load_lds_dwordx4 v254, s[98:99]
	s_add_i32 m0, s14, 0x1000
	s_add_u32 s12, s98, s16
	s_addc_u32 s13, s99, 0
	global_load_lds_dwordx4 v254, s[12:13]
	s_add_i32 m0, s14, 0x2000
	s_add_u32 s12, s12, s16
	s_addc_u32 s13, s13, 0
	global_load_lds_dwordx4 v254, s[12:13]
	s_add_i32 m0, s14, 0x3000
	s_add_u32 s12, s12, s16
	s_addc_u32 s13, s13, 0
	global_load_lds_dwordx4 v254, s[12:13]
	s_add_u32 s98, s98, 0x80
	s_addc_u32 s99, s99, 0
	ds_read_b128 v[188:191], v137
	ds_read_b128 v[64:67], v143 offset:16384
	ds_read_b128 v[68:71], v143 offset:16896
	ds_read_b128 v[72:75], v143 offset:20480
	ds_read_b128 v[76:79], v143 offset:20992
	ds_read_b128 v[192:195], v137 offset:2048
	ds_read_b128 v[246:249], v137 offset:4096
	ds_read_b128 v[250:253], v137 offset:6144
	v_readlane_b32 s10, v245, 0
	s_nop 3
	s_bitcmp0_b32 s10, 8
	s_cbranch_scc1 .Lgk_y_723
	s_setprio 1
	s_branch .Lgk_g_723

; template <class Epi>
; __device__ __forceinline__ void gemm_tile(const bf16_t* __restrict__ A, const bf16_t* __restrict__ Bt, int K, int row0, int col0, const Epi& epi, char* smem,
;                                           bool prefetched, bool nvalid, int nrow0, int ncol0) {
;     ...
;     int offA[4][2], offB[4][2];
; #pragma unroll
;     for (int m = 0; m < 4; ++m)
; #pragma unroll
;         for (int ks = 0; ks < 2; ++ks) { const int cx = ((ks * 4 + fq) ^ ((fr >> 1) & 7)) * 16;
;             offA[m][ks] = (wr * 64 + m * 16 + fr) * 128 + cx;
;             offB[m][ks] = TILE_B + (wc * 64 + (m >> 1) * 32 + 8 * (fr >> 2) + 4 * (m & 1) + (fr & 3)) * 128 + cx; }
;     if (prefetched) {
;         if (Epi::STAGED) asm volatile("s_waitcnt vmcnt(8)" ::: "memory");
;         else asm volatile("s_waitcnt vmcnt(0)" ::: "memory");
;     } else {
;         GLDS_STAGE(0, pA, pB, 0);
;         asm volatile("s_waitcnt vmcnt(0)" ::: "memory");
;     }
;     __syncthreads();
;     const int nk = K >> 6;
;     for (int kt = 0; kt < nk; ++kt) {
;         const int cur = kt & 1;
;         if (kt + 1 < nk) GLDS_STAGE(cur ^ 1, pA, pB, kt + 1);
;         const char* cb = smem + cur * 2 * TILE_B;
; #pragma unroll
;         for (int ks = 0; ks < 2; ++ks) {
;             bf16x8 a[4], b[4];
; #pragma unroll
;             for (int m = 0; m < 4; ++m) a[m] = *(const bf16x8*)(cb + offA[m][ks]);
; #pragma unroll
;             for (int n = 0; n < 4; ++n) b[n] = *(const bf16x8*)(cb + offB[n][ks]);
.LBB0_766:
	v_readfirstlane_b32 s98, v106
	v_readfirstlane_b32 s99, v107
	v_readfirstlane_b32 s10, v108
	v_readfirstlane_b32 s100, v120
	v_readfirstlane_b32 s101, v121
	v_readfirstlane_b32 s13, v149
	s_nop 3
	s_sub_u32 s16, s10, s98
	s_and_b32 s98, s98, 0xffffff80
	s_and_b32 s100, s100, 0xffffff80
	s_nop 1
	v_subrev_u32_e32 v254, s98, v106
	v_subrev_u32_e32 v255, s100, v120
	s_add_i32 s12, s13, 0x8000
	s_mov_b32 m0, s12
	s_nop 0
	global_load_lds_dwordx4 v254, s[98:99]
	s_add_i32 m0, s12, 0x1000
	s_add_u32 s10, s98, s16
	s_addc_u32 s11, s99, 0
	global_load_lds_dwordx4 v254, s[10:11]
	s_add_i32 m0, s12, 0x2000
	s_add_u32 s10, s10, s16
	s_addc_u32 s11, s11, 0
	global_load_lds_dwordx4 v254, s[10:11]
	s_add_i32 m0, s12, 0x3000
	s_add_u32 s10, s10, s16
	s_addc_u32 s11, s11, 0
	global_load_lds_dwordx4 v254, s[10:11]
	s_add_u32 s98, s98, 0x80
	s_addc_u32 s99, s99, 0
	ds_read_b128 v[190:193], v128
	ds_read_b128 v[106:109], v131 offset:16384
	ds_read_b128 v[118:121], v131 offset:16896
	ds_read_b128 v[122:125], v131 offset:20480
	ds_read_b128 v[170:173], v131 offset:20992
	ds_read_b128 v[194:197], v128 offset:2048
	ds_read_b128 v[198:201], v128 offset:4096
	ds_read_b128 v[246:249], v128 offset:6144
	v_readlane_b32 s8, v245, 0
	s_nop 3
	s_bitcmp0_b32 s8, 8
	s_cbranch_scc1 .Lgk_y_766
	s_setprio 1
	s_branch .Lgk_g_766

; template <class Epi>
; __device__ __forceinline__ void gemm_tile(const bf16_t* __restrict__ A, const bf16_t* __restrict__ Bt, int K, int row0, int col0, const Epi& epi, char* smem,
;                                           bool prefetched, bool nvalid, int nrow0, int ncol0) {
;     ...
;     int offA[4][2], offB[4][2];
; #pragma unroll
;     for (int m = 0; m < 4; ++m)
; #pragma unroll
;         for (int ks = 0; ks < 2; ++ks) { const int cx = ((ks * 4 + fq) ^ ((fr >> 1) & 7)) * 16;
;             offA[m][ks] = (wr * 64 + m * 16 + fr) * 128 + cx;
;             offB[m][ks] = TILE_B + (wc * 64 + (m >> 1) * 32 + 8 * (fr >> 2) + 4 * (m & 1) + (fr & 3)) * 128 + cx; }
;     if (prefetched) {
;         if (Epi::STAGED) asm volatile("s_waitcnt vmcnt(8)" ::: "memory");
;         else asm volatile("s_waitcnt vmcnt(0)" ::: "memory");
;     } else {
;         GLDS_STAGE(0, pA, pB, 0);
;         asm volatile("s_waitcnt vmcnt(0)" ::: "memory");
;     }
;     __syncthreads();
;     const int nk = K >> 6;
;     for (int kt = 0; kt < nk; ++kt) {
;         const int cur = kt & 1;
;         if (kt + 1 < nk) GLDS_STAGE(cur ^ 1, pA, pB, kt + 1);
;         const char* cb = smem + cur * 2 * TILE_B;
; #pragma unroll
;         for (int ks = 0; ks < 2; ++ks) {
;             bf16x8 a[4], b[4];
; #pragma unroll
;             for (int m = 0; m < 4; ++m) a[m] = *(const bf16x8*)(cb + offA[m][ks]);
; #pragma unroll
;             for (int n = 0; n < 4; ++n) b[n] = *(const bf16x8*)(cb + offB[n][ks]);
.LBB0_998:
	v_readfirstlane_b32 s98, v106
	v_readfirstlane_b32 s99, v107
	v_readfirstlane_b32 s10, v108
	v_readfirstlane_b32 s100, v120
	v_readfirstlane_b32 s101, v121
	v_readfirstlane_b32 s17, v149
	s_nop 3
	s_sub_u32 s18, s10, s98
	s_and_b32 s98, s98, 0xffffff80
	s_and_b32 s100, s100, 0xffffff80
	s_nop 1
	v_subrev_u32_e32 v254, s98, v106
	v_subrev_u32_e32 v255, s100, v120
	s_add_i32 s13, s17, 0x8000
	s_mov_b32 m0, s13
	s_nop 0
	global_load_lds_dwordx4 v254, s[98:99]
	s_add_i32 m0, s13, 0x1000
	s_add_u32 s10, s98, s18
	s_addc_u32 s11, s99, 0
	global_load_lds_dwordx4 v254, s[10:11]
	s_add_i32 m0, s13, 0x2000
	s_add_u32 s10, s10, s18
	s_addc_u32 s11, s11, 0
	global_load_lds_dwordx4 v254, s[10:11]
	s_add_i32 m0, s13, 0x3000
	s_add_u32 s10, s10, s18
	s_addc_u32 s11, s11, 0
	global_load_lds_dwordx4 v254, s[10:11]
	s_add_u32 s98, s98, 0x80
	s_addc_u32 s99, s99, 0
	ds_read_b128 v[184:187], v130
	ds_read_b128 v[106:109], v133 offset:16384
	ds_read_b128 v[118:121], v133 offset:16896
	ds_read_b128 v[122:125], v133 offset:20480
	ds_read_b128 v[158:161], v133 offset:20992
	ds_read_b128 v[188:191], v130 offset:2048
	ds_read_b128 v[246:249], v130 offset:4096
	ds_read_b128 v[250:253], v130 offset:6144
	v_readlane_b32 s9, v245, 0
	s_nop 3
	s_bitcmp0_b32 s9, 8
	s_cbranch_scc1 .Lgk_y_998
	s_setprio 1
	s_branch .Lgk_g_998

; template <class Epi>
; __device__ __forceinline__ void gemm_tile(const bf16_t* __restrict__ A, const bf16_t* __restrict__ Bt, int K, int row0, int col0, const Epi& epi, char* smem,
;                                           bool prefetched, bool nvalid, int nrow0, int ncol0) {
;     ...
;     int offA[4][2], offB[4][2];
; #pragma unroll
;     for (int m = 0; m < 4; ++m)
; #pragma unroll
;         for (int ks = 0; ks < 2; ++ks) { const int cx = ((ks * 4 + fq) ^ ((fr >> 1) & 7)) * 16;
;             offA[m][ks] = (wr * 64 + m * 16 + fr) * 128 + cx;
;             offB[m][ks] = TILE_B + (wc * 64 + (m >> 1) * 32 + 8 * (fr >> 2) + 4 * (m & 1) + (fr & 3)) * 128 + cx; }
;     if (prefetched) {
;         if (Epi::STAGED) asm volatile("s_waitcnt vmcnt(8)" ::: "memory");
;         else asm volatile("s_waitcnt vmcnt(0)" ::: "memory");
;     } else {
;         GLDS_STAGE(0, pA, pB, 0);
;         asm volatile("s_waitcnt vmcnt(0)" ::: "memory");
;     }
;     __syncthreads();
;     const int nk = K >> 6;
;     for (int kt = 0; kt < nk; ++kt) {
;         const int cur = kt & 1;
;         if (kt + 1 < nk) GLDS_STAGE(cur ^ 1, pA, pB, kt + 1);
;         const char* cb = smem + cur * 2 * TILE_B;
; #pragma unroll
;         for (int ks = 0; ks < 2; ++ks) {
;             bf16x8 a[4], b[4];
; #pragma unroll
;             for (int m = 0; m < 4; ++m) a[m] = *(const bf16x8*)(cb + offA[m][ks]);
; #pragma unroll
;             for (int n = 0; n < 4; ++n) b[n] = *(const bf16x8*)(cb + offB[n][ks]);
.LBB0_1054:
	v_readfirstlane_b32 s98, v92
	v_readfirstlane_b32 s99, v93
	v_readfirstlane_b32 s6, v94
	v_readfirstlane_b32 s100, v100
	v_readfirstlane_b32 s101, v101
	v_readfirstlane_b32 s10, v149
	s_nop 3
	s_sub_u32 s11, s6, s98
	s_and_b32 s98, s98, 0xffffff80
	s_and_b32 s100, s100, 0xffffff80
	s_nop 1
	v_subrev_u32_e32 v254, s98, v92
	v_subrev_u32_e32 v255, s100, v100
	s_add_i32 s9, s10, 0x8000
	s_mov_b32 m0, s9
	s_nop 0
	global_load_lds_dwordx4 v254, s[98:99]
	s_add_i32 m0, s9, 0x1000
	s_add_u32 s6, s98, s11
	s_addc_u32 s7, s99, 0
	global_load_lds_dwordx4 v254, s[6:7]
	s_add_i32 m0, s9, 0x2000
	s_add_u32 s6, s6, s11
	s_addc_u32 s7, s7, 0
	global_load_lds_dwordx4 v254, s[6:7]
	s_add_i32 m0, s9, 0x3000
	s_add_u32 s6, s6, s11
	s_addc_u32 s7, s7, 0
	global_load_lds_dwordx4 v254, s[6:7]
	s_add_u32 s98, s98, 0x80
	s_addc_u32 s99, s99, 0
	ds_read_b128 v[150:153], v108
	ds_read_b128 v[92:95], v110 offset:16384
	ds_read_b128 v[96:99], v110 offset:16896
	ds_read_b128 v[100:103], v110 offset:20480
	ds_read_b128 v[104:107], v110 offset:20992
	ds_read_b128 v[154:157], v108 offset:2048
	ds_read_b128 v[246:249], v108 offset:4096
	ds_read_b128 v[250:253], v108 offset:6144
	v_readlane_b32 s3, v245, 0
	s_nop 3
	s_bitcmp0_b32 s3, 8
	s_cbranch_scc1 .Lgk_y_1054
	s_setprio 1
	s_branch .Lgk_g_1054
